# v55 + retention causal-mask stage: compare against inline constants on a single row-minus-column value, four rotating mask registers, no per-element adds or hazard nops
# baseline (speedup 1.0000x reference)
.Lret_d1_end:
	s_mov_b64 s[16:17], -1
	s_and_b64 vcc, exec, s[54:55]
	s_cbranch_vccz .LBB0_1003
	v_lshlrev_b32_e32 v4, 2, v233
	v_add_u32_e32 v2, v234, v205
	v_add_u32_e32 v5, v4, v209
	s_barrier
	v_add_u32_e32 v4, v4, v210
	v_sub_u32_e32 v7, v2, v5
	v_sub_u32_e32 v10, v2, v4
	v_mul_lo_u32 v3, v2, s68
	v_lshl_add_u32 v6, v5, 1, v3
	v_lshl_add_u32 v3, v4, 1, v3
	s_and_saveexec_b64 s[16:17], s[10:11]
	s_cbranch_execz .Lre_m1
	v_cmp_le_i32_e64 s[82:83], 0, v7
	v_cmp_le_i32_e64 s[96:97], 1, v7
	v_cmp_le_i32_e64 s[58:59], 2, v7
	v_cmp_le_i32_e32 vcc, 3, v7
	v_cndmask_b32_e64 v128, 0, v128, s[82:83]
	v_cndmask_b32_e64 v129, 0, v129, s[96:97]
	v_cndmask_b32_e64 v130, 0, v130, s[58:59]
	v_cndmask_b32_e32 v131, 0, v131, vcc
	v_cmp_le_i32_e64 s[82:83], 8, v7
	v_cmp_le_i32_e64 s[96:97], 9, v7
	v_cmp_le_i32_e64 s[58:59], 10, v7
	v_cmp_le_i32_e32 vcc, 11, v7
	v_cndmask_b32_e64 v132, 0, v132, s[82:83]
	v_cndmask_b32_e64 v133, 0, v133, s[96:97]
	v_cndmask_b32_e64 v134, 0, v134, s[58:59]
	v_cndmask_b32_e32 v135, 0, v135, vcc
	v_cmp_le_i32_e64 s[82:83], 16, v7
	v_cmp_le_i32_e64 s[96:97], 17, v7
	v_cmp_le_i32_e64 s[58:59], 18, v7
	v_cmp_le_i32_e32 vcc, 19, v7
	v_cndmask_b32_e64 v136, 0, v136, s[82:83]
	v_cndmask_b32_e64 v137, 0, v137, s[96:97]
	v_cndmask_b32_e64 v138, 0, v138, s[58:59]
	v_cndmask_b32_e32 v139, 0, v139, vcc
	v_cmp_le_i32_e64 s[82:83], 24, v7
	v_cmp_le_i32_e64 s[96:97], 25, v7
	v_cmp_le_i32_e64 s[58:59], 26, v7
	v_cmp_le_i32_e32 vcc, 27, v7
	v_cndmask_b32_e64 v140, 0, v140, s[82:83]
	v_cndmask_b32_e64 v141, 0, v141, s[96:97]
	v_cndmask_b32_e64 v142, 0, v142, s[58:59]
	v_cndmask_b32_e32 v143, 0, v143, vcc
.Lre_m1:
	s_or_b64 exec, exec, s[16:17]
	v_cvt_pk_bf16_f32 v8, v128, v129
	v_cvt_pk_bf16_f32 v9, v130, v131
	ds_write_b64 v6, v[8:9]
	v_cvt_pk_bf16_f32 v12, v132, v133
	v_cvt_pk_bf16_f32 v13, v134, v135
	ds_write_b64 v6, v[12:13] offset:16
	v_cvt_pk_bf16_f32 v8, v136, v137
	v_cvt_pk_bf16_f32 v9, v138, v139
	ds_write_b64 v6, v[8:9] offset:32
	v_cvt_pk_bf16_f32 v12, v140, v141
	v_cvt_pk_bf16_f32 v13, v142, v143
	ds_write_b64 v6, v[12:13] offset:48
	s_and_saveexec_b64 s[16:17], s[12:13]
	s_cbranch_execz .Lre_m2
	v_cmp_le_i32_e64 s[82:83], 0, v10
	v_cmp_le_i32_e64 s[96:97], 1, v10
	v_cmp_le_i32_e64 s[58:59], 2, v10
	v_cmp_le_i32_e32 vcc, 3, v10
	v_cndmask_b32_e64 v112, 0, v112, s[82:83]
	v_cndmask_b32_e64 v113, 0, v113, s[96:97]
	v_cndmask_b32_e64 v114, 0, v114, s[58:59]
	v_cndmask_b32_e32 v115, 0, v115, vcc
	v_cmp_le_i32_e64 s[82:83], 8, v10
	v_cmp_le_i32_e64 s[96:97], 9, v10
	v_cmp_le_i32_e64 s[58:59], 10, v10
	v_cmp_le_i32_e32 vcc, 11, v10
	v_cndmask_b32_e64 v116, 0, v116, s[82:83]
	v_cndmask_b32_e64 v117, 0, v117, s[96:97]
	v_cndmask_b32_e64 v118, 0, v118, s[58:59]
	v_cndmask_b32_e32 v119, 0, v119, vcc
	v_cmp_le_i32_e64 s[82:83], 16, v10
	v_cmp_le_i32_e64 s[96:97], 17, v10
	v_cmp_le_i32_e64 s[58:59], 18, v10
	v_cmp_le_i32_e32 vcc, 19, v10
	v_cndmask_b32_e64 v120, 0, v120, s[82:83]
	v_cndmask_b32_e64 v121, 0, v121, s[96:97]
	v_cndmask_b32_e64 v122, 0, v122, s[58:59]
	v_cndmask_b32_e32 v123, 0, v123, vcc
	v_cmp_le_i32_e64 s[82:83], 24, v10
	v_cmp_le_i32_e64 s[96:97], 25, v10
	v_cmp_le_i32_e64 s[58:59], 26, v10
	v_cmp_le_i32_e32 vcc, 27, v10
	v_cndmask_b32_e64 v124, 0, v124, s[82:83]
	v_cndmask_b32_e64 v125, 0, v125, s[96:97]
	v_cndmask_b32_e64 v126, 0, v126, s[58:59]
	v_cndmask_b32_e32 v127, 0, v127, vcc
.Lre_m2:
	s_or_b64 exec, exec, s[16:17]
	v_cvt_pk_bf16_f32 v8, v112, v113
	v_cvt_pk_bf16_f32 v9, v114, v115
	ds_write_b64 v3, v[8:9]
	v_cvt_pk_bf16_f32 v12, v116, v117
	v_cvt_pk_bf16_f32 v13, v118, v119
	ds_write_b64 v3, v[12:13] offset:16
	v_cvt_pk_bf16_f32 v8, v120, v121
	v_cvt_pk_bf16_f32 v9, v122, v123
	ds_write_b64 v3, v[8:9] offset:32
	v_cvt_pk_bf16_f32 v12, v124, v125
	v_cvt_pk_bf16_f32 v13, v126, v127
	ds_write_b64 v3, v[12:13] offset:48
	s_and_b64 vcc, exec, s[56:57]
	s_waitcnt lgkmcnt(0)
	s_barrier
	s_cbranch_vccz .LBB0_974
	v_mov_b32_e32 v2, s33
	v_cndmask_b32_e64 v1, v2, v1, s[44:45]
	v_lshlrev_b32_e32 v2, 7, v1
	v_mov_b32_e32 v1, v202
	v_mov_b32_e32 v3, v0
	v_sub_u32_e32 v4, 0x7f, v1
	v_cndmask_b32_e64 v4, v4, v1, s[44:45]
	v_sub_u32_e32 v6, 0x5f, v1
	v_add_u32_e32 v7, 32, v1
	v_lshlrev_b64 v[2:3], 12, v[2:3]
	v_lshl_or_b32 v4, v4, 11, v203
	v_cndmask_b32_e64 v6, v6, v7, s[44:45]
	v_lshl_add_u64 v[2:3], s[42:43], 0, v[2:3]
	v_ashrrev_i32_e32 v5, 31, v4
	v_lshl_or_b32 v6, v6, 11, v203
	v_lshl_add_u64 v[4:5], v[4:5], 1, v[2:3]
	v_ashrrev_i32_e32 v7, 31, v6
	v_lshl_add_u64 v[6:7], v[6:7], 1, v[2:3]
	global_load_dwordx4 v[160:163], v[4:5], off
	global_load_dwordx4 v[164:167], v[6:7], off
	v_sub_u32_e32 v4, 63, v1
	v_add_u32_e32 v5, 64, v1
	v_cndmask_b32_e64 v4, v4, v5, s[44:45]
	v_sub_u32_e32 v6, 31, v1
	v_add_u32_e32 v1, 0x60, v1
	v_lshl_or_b32 v4, v4, 11, v203
	v_cndmask_b32_e64 v1, v6, v1, s[44:45]
	v_ashrrev_i32_e32 v5, 31, v4
	v_lshl_or_b32 v6, v1, 11, v203
	v_lshl_add_u64 v[4:5], v[4:5], 1, v[2:3]
	v_ashrrev_i32_e32 v7, 31, v6
	v_lshl_add_u64 v[2:3], v[6:7], 1, v[2:3]
	global_load_dwordx4 v[168:171], v[4:5], off
	global_load_dwordx4 v[172:175], v[2:3], off
